# P4 LoRA prefix item: next column block's weight fragments prefetched into cache one inner iteration ahead
# baseline (speedup 1.0000x reference)
.LBB0_898:
	v_lshlrev_b64 v[138:139], 1, v[110:111]
	v_mov_b32_e32 v123, v111
	v_mov_b32_e32 v121, v111
	v_lshl_add_u64 v[180:181], v[112:113], 0, v[138:139]
	v_lshl_add_u64 v[188:189], v[114:115], 0, v[138:139]
	v_mov_b64_e32 v[248:249], v[180:181]
	v_mov_b64_e32 v[252:253], v[188:189]
	v_lshl_add_u64 v[202:203], v[122:123], 1, v[116:117]
	v_lshlrev_b64 v[216:217], 2, v[120:121]
	global_load_dwordx4 v[138:141], v[202:203], off
	global_load_dwordx4 v[142:145], v[180:181], off
	global_load_dwordx4 v[174:177], v[188:189], off
	s_nop 0
	global_load_dwordx4 v[180:183], v[180:181], off offset:64
	s_nop 0
	global_load_dwordx4 v[184:187], v[202:203], off offset:64
	s_nop 0
	global_load_dwordx4 v[188:191], v[188:189], off offset:64
	s_nop 0
	global_load_dwordx4 v[192:195], v[202:203], off offset:128
	global_load_dwordx4 v[196:199], v[202:203], off offset:192
	global_load_dwordx4 v[212:215], v[202:203], off offset:256
	s_mov_b64 s[98:99], 0x1400
	v_lshl_add_u64 v[250:251], v[202:203], 0, s[98:99]
	v_lshl_add_u64 v[202:203], s[36:37], 0, v[216:217]
	v_lshl_add_u64 v[218:219], v[124:125], 0, v[120:121]
	v_lshl_add_u64 v[220:221], v[126:127], 0, v[120:121]
	v_lshl_add_u64 v[222:223], v[128:129], 0, v[120:121]
	v_lshl_add_u64 v[224:225], v[130:131], 0, v[120:121]
	v_lshl_add_u64 v[216:217], s[40:41], 0, v[216:217]
	global_load_dword v121, v[202:203], off
	global_load_dword v123, v[216:217], off
	global_load_dwordx4 v[244:247], v[250:251], off
	global_load_dwordx4 v[244:247], v[250:251], off offset:64
	global_load_dwordx4 v[244:247], v[250:251], off offset:128
	global_load_dwordx4 v[244:247], v[250:251], off offset:192
	global_load_dwordx4 v[244:247], v[250:251], off offset:256
	global_load_dwordx4 v[244:247], v[248:249], off offset:2048
	global_load_dwordx4 v[244:247], v[248:249], off offset:2112
	global_load_dwordx4 v[244:247], v[252:253], off offset:2048
	global_load_dwordx4 v[244:247], v[252:253], off offset:2112
	s_add_i32 s0, s0, -1
	v_lshlrev_b64 v[218:219], 1, v[218:219]
	v_add_u32_e32 v110, 0x400, v110
	v_add_u32_e32 v120, 16, v120
	v_add_u32_e32 v122, 0xa00, v122
	s_cmp_eq_u32 s0, 0
	v_lshlrev_b64 v[220:221], 1, v[220:221]
	v_lshlrev_b64 v[222:223], 1, v[222:223]
	v_lshlrev_b64 v[224:225], 1, v[224:225]
	v_lshl_add_u64 v[202:203], s[4:5], 0, v[218:219]
	v_lshl_add_u64 v[216:217], s[16:17], 0, v[218:219]
	v_lshl_add_u64 v[218:219], s[42:43], 0, v[218:219]
	s_waitcnt vmcnt(19)
	v_mfma_f32_16x16x32_bf16 v[138:141], v[94:97], v[138:141], 0
	s_waitcnt vmcnt(18)
	v_mfma_f32_16x16x32_bf16 v[142:145], v[102:105], v[142:145], 0
	s_waitcnt vmcnt(17)
	v_mfma_f32_16x16x32_bf16 v[174:177], v[78:81], v[174:177], 0
	s_waitcnt vmcnt(16)
	v_mfma_f32_16x16x32_bf16 v[142:145], v[98:101], v[180:183], v[142:145]
	v_lshl_add_u64 v[180:181], s[4:5], 0, v[222:223]
	v_lshl_add_u64 v[182:183], s[16:17], 0, v[222:223]
	v_lshl_add_u64 v[222:223], s[42:43], 0, v[222:223]
	s_waitcnt vmcnt(15)
	v_mfma_f32_16x16x32_bf16 v[138:141], v[90:93], v[184:187], v[138:141]
	v_lshl_add_u64 v[184:185], s[4:5], 0, v[220:221]
	s_waitcnt vmcnt(10)
	s_nop 0
	v_add_f32_e32 v142, v121, v142
	v_add_f32_e32 v143, v121, v143
	v_mfma_f32_16x16x32_bf16 v[174:177], v[86:89], v[188:191], v[174:177]
	v_add_f32_e32 v144, v121, v144
	v_add_f32_e32 v121, v121, v145
	v_mul_f32_e32 v142, 0xbfb8aa3b, v142
	v_mfma_f32_16x16x32_bf16 v[138:141], v[82:85], v[192:195], v[138:141]
	v_mul_f32_e32 v143, 0xbfb8aa3b, v143
	s_waitcnt vmcnt(9)
	s_nop 1
	v_add_f32_e32 v147, v123, v174
	v_add_f32_e32 v149, v123, v175
	v_add_f32_e32 v151, v123, v176
	v_add_f32_e32 v123, v123, v177
	v_mul_f32_e32 v145, 0xbfb8aa3b, v147
	v_mul_f32_e32 v147, 0xbfb8aa3b, v149
	v_mul_f32_e32 v144, 0xbfb8aa3b, v144
	v_mul_f32_e32 v149, 0xbfb8aa3b, v151
	v_mul_f32_e32 v121, 0xbfb8aa3b, v121
	v_mul_f32_e32 v123, 0xbfb8aa3b, v123
	v_exp_f32_e32 v142, v142
	v_exp_f32_e32 v145, v145
	v_exp_f32_e32 v143, v143
	v_exp_f32_e32 v147, v147
	v_exp_f32_e32 v144, v144
	v_exp_f32_e32 v149, v149
	v_exp_f32_e32 v121, v121
	v_exp_f32_e32 v123, v123
	v_mfma_f32_16x16x32_bf16 v[138:141], v[74:77], v[196:199], v[138:141]
	v_add_f32_e32 v142, 1.0, v142
	v_add_f32_e32 v145, 1.0, v145
	v_add_f32_e32 v143, 1.0, v143
	v_add_f32_e32 v147, 1.0, v147
	v_add_f32_e32 v144, 1.0, v144
	v_add_f32_e32 v149, 1.0, v149
	v_add_f32_e32 v121, 1.0, v121
	v_add_f32_e32 v123, 1.0, v123
	v_rcp_f32_e32 v142, v142
	v_rcp_f32_e32 v145, v145
	v_rcp_f32_e32 v143, v143
	v_rcp_f32_e32 v147, v147
	v_rcp_f32_e32 v144, v144
	v_rcp_f32_e32 v149, v149
	v_rcp_f32_e32 v121, v121
	v_rcp_f32_e32 v123, v123
	v_mfma_f32_16x16x32_bf16 v[138:141], v[106:109], v[212:215], v[138:141]
	v_mul_f32_e32 v142, 0x3f1b4598, v142
	v_bfe_u32 v151, v145, 16, 1
	v_mul_f32_e32 v143, 0x3f1b4598, v143
	v_bfe_u32 v153, v147, 16, 1
	v_mul_f32_e32 v144, 0x3f1b4598, v144
	v_bfe_u32 v157, v149, 16, 1
	v_mul_f32_e32 v121, 0x3f1b4598, v121
	v_bfe_u32 v159, v123, 16, 1
	v_bfe_u32 v161, v142, 16, 1
	v_add3_u32 v145, v145, v151, s66
	v_bfe_u32 v151, v138, 16, 1
	v_bfe_u32 v163, v143, 16, 1
	v_add3_u32 v147, v147, v153, s66
	v_bfe_u32 v153, v139, 16, 1
	v_bfe_u32 v165, v144, 16, 1
	v_add3_u32 v149, v149, v157, s66
	v_bfe_u32 v157, v140, 16, 1
	v_bfe_u32 v171, v121, 16, 1
	v_add3_u32 v123, v123, v159, s66
	v_bfe_u32 v159, v141, 16, 1
	v_add3_u32 v142, v142, v161, s66
	v_lshl_add_u64 v[186:187], s[16:17], 0, v[220:221]
	v_lshl_add_u64 v[220:221], s[42:43], 0, v[220:221]
	v_lshl_add_u64 v[188:189], s[4:5], 0, v[224:225]
	v_lshl_add_u64 v[190:191], s[16:17], 0, v[224:225]
	v_lshl_add_u64 v[224:225], s[42:43], 0, v[224:225]
	global_store_short_d16_hi v[216:217], v145, off
	v_add3_u32 v138, v138, v151, s66
	v_add3_u32 v143, v143, v163, s66
	v_add3_u32 v139, v139, v153, s66
	v_add3_u32 v144, v144, v165, s66
	v_add3_u32 v140, v140, v157, s66
	v_add3_u32 v121, v121, v171, s66
	v_add3_u32 v141, v141, v159, s66
	global_store_short_d16_hi v[202:203], v142, off
	global_store_short_d16_hi v[218:219], v138, off
	global_store_short_d16_hi v[184:185], v143, off
	global_store_short_d16_hi v[186:187], v147, off
	global_store_short_d16_hi v[220:221], v139, off
	global_store_short_d16_hi v[180:181], v144, off
	global_store_short_d16_hi v[182:183], v149, off
	global_store_short_d16_hi v[222:223], v140, off
	global_store_short_d16_hi v[188:189], v121, off
	global_store_short_d16_hi v[190:191], v123, off
	global_store_short_d16_hi v[224:225], v141, off
	s_cbranch_scc0 .LBB0_898
	s_add_i32 s10, s10, s88
	s_add_i32 s11, s11, s31
	s_cmpk_gt_i32 s10, 0x103
	s_cbranch_scc0 .LBB0_815

	.amdhsa_kernel _Z10fwd_kernel4Args
		.amdhsa_group_segment_fixed_size 0
		.amdhsa_private_segment_fixed_size 0
		.amdhsa_kernarg_size 520
		.amdhsa_user_sgpr_count 2
		.amdhsa_user_sgpr_dispatch_ptr 0
		.amdhsa_user_sgpr_queue_ptr 0
		.amdhsa_user_sgpr_kernarg_segment_ptr 1
		.amdhsa_user_sgpr_dispatch_id 0
		.amdhsa_user_sgpr_kernarg_preload_length 0
		.amdhsa_user_sgpr_kernarg_preload_offset 0
		.amdhsa_user_sgpr_private_segment_size 0
		.amdhsa_uses_dynamic_stack 0
		.amdhsa_enable_private_segment 0
		.amdhsa_system_sgpr_workgroup_id_x 1
		.amdhsa_system_sgpr_workgroup_id_y 0
		.amdhsa_system_sgpr_workgroup_id_z 0
		.amdhsa_system_sgpr_workgroup_info 0
		.amdhsa_system_vgpr_workitem_id 0
		.amdhsa_next_free_vgpr 256
		.amdhsa_next_free_sgpr 100
		.amdhsa_accum_offset 256
		.amdhsa_reserve_vcc 1
		.amdhsa_float_round_mode_32 0
		.amdhsa_float_round_mode_16_64 0
		.amdhsa_float_denorm_mode_32 3
		.amdhsa_float_denorm_mode_16_64 3
		.amdhsa_dx10_clamp 1
		.amdhsa_ieee_mode 1
		.amdhsa_fp16_overflow 0
		.amdhsa_tg_split 0
		.amdhsa_exception_fp_ieee_invalid_op 0
		.amdhsa_exception_fp_denorm_src 0
		.amdhsa_exception_fp_ieee_div_zero 0
		.amdhsa_exception_fp_ieee_overflow 0
		.amdhsa_exception_fp_ieee_underflow 0
		.amdhsa_exception_fp_ieee_inexact 0
		.amdhsa_exception_int_div_zero 0
	.end_amdhsa_kernel

amdhsa.kernels:
  - .agpr_count:     0
    .args:
      - .offset:         0
        .size:           264
        .value_kind:     by_value
      - .offset:         264
        .size:           4
        .value_kind:     hidden_block_count_x
      - .offset:         268
        .size:           4
        .value_kind:     hidden_block_count_y
      - .offset:         272
        .size:           4
        .value_kind:     hidden_block_count_z
      - .offset:         276
        .size:           2
        .value_kind:     hidden_group_size_x
      - .offset:         278
        .size:           2
        .value_kind:     hidden_group_size_y
      - .offset:         280
        .size:           2
        .value_kind:     hidden_group_size_z
      - .offset:         282
        .size:           2
        .value_kind:     hidden_remainder_x
      - .offset:         284
        .size:           2
        .value_kind:     hidden_remainder_y
      - .offset:         286
        .size:           2
        .value_kind:     hidden_remainder_z
      - .offset:         304
        .size:           8
        .value_kind:     hidden_global_offset_x
      - .offset:         312
        .size:           8
        .value_kind:     hidden_global_offset_y
      - .offset:         320
        .size:           8
        .value_kind:     hidden_global_offset_z
      - .offset:         328
        .size:           2
        .value_kind:     hidden_grid_dims
      - .offset:         384
        .size:           4
        .value_kind:     hidden_dynamic_lds_size
    .group_segment_fixed_size: 0
    .kernarg_segment_align: 8
    .kernarg_segment_size: 520
    .language:       OpenCL C
    .language_version:
      - 2
      - 0
    .max_flat_workgroup_size: 512
    .name:           _Z10fwd_kernel4Args
    .private_segment_fixed_size: 0
    .sgpr_count:     106
    .sgpr_spill_count: 48
    .symbol:         _Z10fwd_kernel4Args.kd
    .uniform_work_group_size: 1
    .uses_dynamic_stack: false
    .vgpr_count:     256
    .vgpr_spill_count: 0
    .wavefront_size: 64
